# previous plus first K-iteration peeled for non-residual GEMM kinds: first MFMA of every accumulator takes C=0, the 128-register VALU zero-init per unit and the per-unit vmcnt(0) are gone
# speedup vs baseline: 1.0135x; 1.0075x over previous
; __device__ __forceinline__ void res_init(const float* base, bool bf, f32x4 (&acc)[2][2][4][2], const Unit& u, int wr, int wc, int fr, int fq) {
;         const int row0 = u.pm * BM + wr * 64 + fr, col0 = u.pn * BM + wc * 32 + 8 * fq;
;         if (!bf) {
; #pragma unroll
;             for (int ai = 0; ai < 2; ++ai)
; #pragma unroll
;                 for (int m = 0; m < 4; ++m) { const size_t off = (size_t)(row0 + ai * HALF + m * 16) * 1024 + col0;
; #pragma unroll
;                     for (int bj = 0; bj < 2; ++bj)
; #pragma unroll
;                         for (int n = 0; n < 2; ++n) acc[ai][bj][m][n] = *(const f32x4*)(base + off + bj * HALF + n * 4); }
;     __device__ __forceinline__ void init(f32x4 (&acc)[2][2][4][2], const Unit& u, int wr, int wc, int fr, int fq) const {
;         if (kind == 2) res_init(base, (gi >> 2) != 0, acc, u, wr, wc, fr, fq);
;         else {
; #pragma unroll
;             for (int a = 0; a < 2; ++a)
; #pragma unroll
;                 for (int b = 0; b < 2; ++b)
; #pragma unroll
;                     for (int m = 0; m < 4; ++m)
; #pragma unroll
;                         for (int n = 0; n < 2; ++n) acc[a][b][m][n] = (f32x4){0.f, 0.f, 0.f, 0.f}; }
.LBB0_246:
	s_andn2_b64 vcc, exec, s[12:13]
	s_cbranch_vccnz .LBB0_382
	s_ashr_i32 s12, s17, 6
	s_and_b32 s34, s12, 3
	v_bfe_u32 v143, v80, 4, 2
	s_ashr_i32 s21, s17, 8
	v_cndmask_b32_e64 v0, 0, 1, s[0:1]
	v_and_b32_e32 v243, 15, v80
	s_lshl_b32 s66, s21, 6
	v_lshlrev_b32_e32 v142, 3, v143
	s_lshl_b32 s35, s34, 5
	v_cmp_ne_u32_e64 s[40:41], 1, v0
	s_andn2_b64 vcc, exec, s[0:1]
	s_waitcnt vmcnt(14)
	s_waitcnt vmcnt(10)
	s_waitcnt vmcnt(6)
	s_waitcnt vmcnt(4)
	s_cbranch_vccnz .LBB0_252
	s_lshl_b32 s0, s88, 8
	s_lshl_b32 s1, s87, 8
	s_add_i32 s0, s0, s66
	s_or_b32 s1, s1, s35
	v_or_b32_e32 v134, s0, v243
	v_or_b32_e32 v136, s1, v142
	s_cmp_gt_u32 s18, 3
	v_ashrrev_i32_e32 v137, 31, v136
	v_ashrrev_i32_e32 v135, 31, v134
	s_mov_b64 s[0:1], -1
	v_or_b32_e32 v138, 16, v134
	v_or_b32_e32 v132, 32, v134
	v_or_b32_e32 v130, 48, v134
	s_cbranch_scc1 .LBB0_250
	v_readlane_b32 s0, v254, 0
	v_readlane_b32 s1, v254, 1
	v_lshlrev_b64 v[0:1], 12, v[134:135]
	v_ashrrev_i32_e32 v139, 31, v138
	v_lshl_add_u64 v[48:49], v[136:137], 2, s[0:1]
	v_lshl_add_u64 v[114:115], v[48:49], 0, v[0:1]
	s_mov_b64 s[0:1], 0x80000
	v_lshl_add_u64 v[76:77], v[114:115], 0, s[0:1]
	s_mov_b32 s0, 0x80000
	v_add_co_u32_e32 v64, vcc, s0, v114
	s_mov_b64 s[0:1], 0x90000
	s_nop 0
	v_addc_co_u32_e32 v65, vcc, 0, v115, vcc
	v_lshl_add_u64 v[94:95], v[114:115], 0, s[0:1]
	s_mov_b32 s0, 0x90000
	v_add_co_u32_e32 v82, vcc, s0, v114
	s_mov_b64 s[0:1], 0xa0000
	s_nop 0
	v_addc_co_u32_e32 v83, vcc, 0, v115, vcc
	v_lshl_add_u64 v[110:111], v[114:115], 0, s[0:1]
	s_mov_b32 s0, 0xa0000
	v_add_co_u32_e32 v98, vcc, s0, v114
	s_mov_b64 s[0:1], 0xb0000
	v_ashrrev_i32_e32 v133, 31, v132
	v_ashrrev_i32_e32 v131, 31, v130
	v_addc_co_u32_e32 v99, vcc, 0, v115, vcc
	v_lshl_add_u64 v[126:127], v[114:115], 0, s[0:1]
	s_mov_b32 s0, 0xb0000
	global_load_dwordx4 v[0:3], v[114:115], off offset:16
	global_load_dwordx4 v[4:7], v[114:115], off
	global_load_dwordx4 v[8:11], v[114:115], off offset:528
	global_load_dwordx4 v[12:15], v[114:115], off offset:512
	v_lshlrev_b64 v[16:17], 12, v[138:139]
	v_lshlrev_b64 v[32:33], 12, v[132:133]
	v_lshlrev_b64 v[50:51], 12, v[130:131]
	v_add_co_u32_e32 v114, vcc, s0, v114
	v_lshl_add_u64 v[28:29], v[48:49], 0, v[16:17]
	v_lshl_add_u64 v[44:45], v[48:49], 0, v[32:33]
	v_lshl_add_u64 v[60:61], v[48:49], 0, v[50:51]
	v_addc_co_u32_e32 v115, vcc, 0, v115, vcc
	global_load_dwordx4 v[16:19], v[28:29], off offset:16
	global_load_dwordx4 v[20:23], v[28:29], off
	global_load_dwordx4 v[24:27], v[28:29], off offset:528
	s_nop 0
	global_load_dwordx4 v[28:31], v[28:29], off offset:512
	s_nop 0
	global_load_dwordx4 v[32:35], v[44:45], off offset:16
	global_load_dwordx4 v[36:39], v[44:45], off
	global_load_dwordx4 v[40:43], v[44:45], off offset:528
	s_nop 0
	global_load_dwordx4 v[44:47], v[44:45], off offset:512
	s_nop 0
	global_load_dwordx4 v[48:51], v[60:61], off offset:16
	global_load_dwordx4 v[52:55], v[60:61], off
	global_load_dwordx4 v[56:59], v[60:61], off offset:528
	s_nop 0
	global_load_dwordx4 v[60:63], v[60:61], off offset:512
	s_nop 0
	global_load_dwordx4 v[64:67], v[64:65], off
	s_nop 0
	global_load_dwordx4 v[72:75], v[76:77], off offset:528
	global_load_dwordx4 v[68:71], v[76:77], off offset:16
	s_nop 0
	global_load_dwordx4 v[76:79], v[76:77], off offset:512
	s_nop 0
	global_load_dwordx4 v[82:85], v[82:83], off
	s_nop 0
	global_load_dwordx4 v[90:93], v[94:95], off offset:528
	global_load_dwordx4 v[86:89], v[94:95], off offset:16
	s_nop 0
	global_load_dwordx4 v[94:97], v[94:95], off offset:512
	s_nop 0
	global_load_dwordx4 v[98:101], v[98:99], off
	s_nop 0
	global_load_dwordx4 v[106:109], v[110:111], off offset:528
	global_load_dwordx4 v[102:105], v[110:111], off offset:16
	s_nop 0
	global_load_dwordx4 v[110:113], v[110:111], off offset:512
	s_nop 0
	global_load_dwordx4 v[114:117], v[114:115], off
	s_nop 0
	global_load_dwordx4 v[122:125], v[126:127], off offset:528
	global_load_dwordx4 v[118:121], v[126:127], off offset:16
	s_nop 0
	global_load_dwordx4 v[126:129], v[126:127], off offset:512
	s_mov_b64 s[0:1], 0

; #define PG8_STAGE(bufoff, gbase, voff) do { _Pragma("unroll") for (int _i = 0; _i < 2; ++_i) \
;         __builtin_amdgcn_global_load_lds((const unsigned*)((const char*)(gbase) + (voff)[_i]), (PG8_LAS unsigned*)(lds + (bufoff) + ldsw + _i * 8192), 16, 0, 0); } while (0)
; #define PG8_LDA(dst, b, h) do { _Pragma("unroll") for (int m = 0; m < 4; ++m) _Pragma("unroll") for (int k = 0; k < 2; ++k) dst[m][k] = *(const PG8_LAS bf16x8*)(lds + PG8_SA(b, h) + aoff + m * 2048 + k * 1024); } while (0)
; #define PG8_LDB(dst, b, h) do { _Pragma("unroll") for (int n = 0; n < 2; ++n) _Pragma("unroll") for (int k = 0; k < 2; ++k) dst[n][k] = *(const PG8_LAS bf16x8*)(lds + PG8_SB(b, h) + boff + n * 2048 + k * 1024); } while (0)
; #define PG8_MMA(ai, bj, At, Bt) do { __builtin_amdgcn_s_setprio(1); _Pragma("unroll") for (int m = 0; m < 4; ++m) _Pragma("unroll") for (int n = 0; n < 2; ++n) _Pragma("unroll") for (int k = 0; k < 2; ++k) \
;         acc[ai][bj][m][n] = __builtin_amdgcn_mfma_f32_16x16x32_bf16(Bt[n][k], At[m][k], acc[ai][bj][m][n], 0, 0, 0); __builtin_amdgcn_s_setprio(0); } while (0)
; #define PG8_WAIT_V(n) asm volatile("s_waitcnt vmcnt(" #n ")" ::: "memory")
; #define PG8_WAIT_L(n) asm volatile("s_waitcnt lgkmcnt(" #n ")" ::: "memory")
; #define PG8_BAR __builtin_amdgcn_s_barrier()
; #define PG8_SCHED __builtin_amdgcn_sched_barrier(0)
; template <class Epi, class Sched, bool ALIGN_EPI = false>
; __device__ __forceinline__ void gemm_phase(PG8_LAS unsigned char* lds, const Gemm g, const Sched& S, const Epi& E, int tid_in) {
;     ...
;             PG8_LDB(B0, 0, 0); PG8_LDB(B1, 0, 1); PG8_SCHED; PG8_LDA(At, 0, 0); PG8_STAGE(PG8_SA(1, 1), a1 + hstepA, voffA);
;             PG8_WAIT_V(8); PG8_WAIT_L(0); PG8_BAR; PG8_MMA(0, 0, At, B0); PG8_MMA(0, 1, At, B1); PG8_BAR; PG8_SCHED;
;             PG8_LDA(At, 0, 1); PG8_STAGE(PG8_SB(0, 0), b2, voffB); PG8_STAGE(PG8_SB(0, 1), b2 + hstepB, voffB); PG8_STAGE(PG8_SA(0, 0), a2, voffA);
;             PG8_WAIT_V(8); PG8_WAIT_L(0); PG8_BAR; PG8_MMA(1, 0, At, B0); PG8_MMA(1, 1, At, B1); PG8_BAR; PG8_SCHED;
;     ...
;         E.init(acc, nxt, wr, wc, fr, fq);
;         cur = nxt; cA = nA; cB = nB; ++ui;
.LBB0_266:
	s_add_u32 s60, s60, 0x80
	s_addc_u32 s61, s61, 0
	s_add_u32 s57, s58, 0x100
	s_addc_u32 s62, s59, 0
	s_mov_b32 s58, 0
	s_cmp_eq_u32 s64, 2
	s_cbranch_scc1 .Lk_nopeel
	s_add_i32 s63, s58, 2
	s_add_u32 s22, s60, 0x80
	s_addc_u32 s23, s61, 0
	s_add_i32 s89, 0, 0x10000
	s_cmp_eq_u32 s77, s58
	s_cselect_b32 s59, s19, s23
	s_cselect_b32 s58, s18, s22
	v_add_u32_e32 v80, s89, v245
	s_cselect_b32 s23, s35, s62
	s_cselect_b32 s22, s34, s57
	s_add_i32 s90, 0, 0x14000
	ds_read_b128 v[130:133], v80
	ds_read_b128 v[134:137], v80 offset:1024
	ds_read_b128 v[138:141], v80 offset:2048
	ds_read_b128 v[142:145], v80 offset:3072
	v_add_u32_e32 v80, s90, v245
	ds_read_b128 v[146:149], v80
	ds_read_b128 v[150:153], v80 offset:1024
	ds_read_b128 v[154:157], v80 offset:2048
	ds_read_b128 v[158:161], v80 offset:3072
	s_mov_b32 m0, s74
	ds_read_b128 v[162:165], v248
	ds_read_b128 v[166:169], v248 offset:1024
	ds_read_b128 v[170:173], v248 offset:2048
	ds_read_b128 v[174:177], v248 offset:3072
	ds_read_b128 v[178:181], v248 offset:4096
	ds_read_b128 v[198:201], v248 offset:5120
	ds_read_b128 v[202:205], v248 offset:6144
	ds_read_b128 v[206:209], v248 offset:7168
	global_load_lds_dwordx4 v184, s[60:61]
	s_mov_b32 m0, s75
	s_nop 0
	global_load_lds_dwordx4 v188, s[60:61]
	s_add_i32 m0, s70, 0xc000
	s_nop 0
	global_load_lds_dwordx4 v194, s[60:61]
	s_add_i32 m0, s70, 0xe000
	s_nop 0
	global_load_lds_dwordx4 v196, s[60:61]
	s_waitcnt vmcnt(8)
	s_waitcnt lgkmcnt(0)
	v_mfma_f32_16x16x32_bf16 v[4:7], v[130:133], v[162:165], 0
	v_mfma_f32_16x16x32_bf16 v[0:3], v[138:141], v[162:165], 0
	s_barrier
	s_setprio 1
	s_waitcnt lgkmcnt(0)
	v_mfma_f32_16x16x32_bf16 v[20:23], v[130:133], v[170:173], 0
	v_mfma_f32_16x16x32_bf16 v[16:19], v[138:141], v[170:173], 0
	v_mfma_f32_16x16x32_bf16 v[36:39], v[130:133], v[178:181], 0
	v_mfma_f32_16x16x32_bf16 v[32:35], v[138:141], v[178:181], 0
	v_mfma_f32_16x16x32_bf16 v[52:55], v[130:133], v[202:205], 0
	v_mfma_f32_16x16x32_bf16 v[48:51], v[138:141], v[202:205], 0
	v_mfma_f32_16x16x32_bf16 v[4:7], v[134:137], v[166:169], v[4:7]
	v_mfma_f32_16x16x32_bf16 v[0:3], v[142:145], v[166:169], v[0:3]
	v_mfma_f32_16x16x32_bf16 v[20:23], v[134:137], v[174:177], v[20:23]
	v_mfma_f32_16x16x32_bf16 v[16:19], v[142:145], v[174:177], v[16:19]
	v_mfma_f32_16x16x32_bf16 v[36:39], v[134:137], v[198:201], v[36:39]
	v_mfma_f32_16x16x32_bf16 v[32:35], v[142:145], v[198:201], v[32:35]
	v_mfma_f32_16x16x32_bf16 v[52:55], v[134:137], v[206:209], v[52:55]
	v_mfma_f32_16x16x32_bf16 v[48:51], v[142:145], v[206:209], v[48:51]
	s_setprio 0
	s_setprio 1
	v_mfma_f32_16x16x32_bf16 v[12:15], v[146:149], v[162:165], 0
	v_mfma_f32_16x16x32_bf16 v[8:11], v[154:157], v[162:165], 0
	v_mfma_f32_16x16x32_bf16 v[28:31], v[146:149], v[170:173], 0
	v_mfma_f32_16x16x32_bf16 v[24:27], v[154:157], v[170:173], 0
	v_mfma_f32_16x16x32_bf16 v[44:47], v[146:149], v[178:181], 0
	v_mfma_f32_16x16x32_bf16 v[40:43], v[154:157], v[178:181], 0
	v_mfma_f32_16x16x32_bf16 v[60:63], v[146:149], v[202:205], 0
	v_mfma_f32_16x16x32_bf16 v[56:59], v[154:157], v[202:205], 0
	v_mfma_f32_16x16x32_bf16 v[12:15], v[150:153], v[166:169], v[12:15]
	v_mfma_f32_16x16x32_bf16 v[8:11], v[158:161], v[166:169], v[8:11]
	v_mfma_f32_16x16x32_bf16 v[28:31], v[150:153], v[174:177], v[28:31]
	v_mfma_f32_16x16x32_bf16 v[24:27], v[158:161], v[174:177], v[24:27]
	v_mfma_f32_16x16x32_bf16 v[44:47], v[150:153], v[198:201], v[44:47]
	v_mfma_f32_16x16x32_bf16 v[40:43], v[158:161], v[198:201], v[40:43]
	v_mfma_f32_16x16x32_bf16 v[60:63], v[150:153], v[206:209], v[60:63]
	v_mfma_f32_16x16x32_bf16 v[56:59], v[158:161], v[206:209], v[56:59]
	s_setprio 0
	s_barrier
	s_add_i32 s89, s89, s69
	s_mov_b64 vcc, s[22:23]
	s_mov_b32 m0, s89
	ds_read_b128 v[162:165], v248 offset:16384
	ds_read_b128 v[166:169], v248 offset:17408
	ds_read_b128 v[170:173], v248 offset:18432
	ds_read_b128 v[174:177], v248 offset:19456
	ds_read_b128 v[178:181], v248 offset:20480
	ds_read_b128 v[198:201], v248 offset:21504
	ds_read_b128 v[202:205], v248 offset:22528
	ds_read_b128 v[206:209], v248 offset:23552
	global_load_lds_dwordx4 v186, s[22:23]
	s_add_i32 m0, s89, 0x2000
	s_add_u32 s22, s22, s33
	s_addc_u32 s23, s23, 0
	s_add_i32 s89, s90, s69
	global_load_lds_dwordx4 v190, vcc
	s_mov_b32 m0, s89
	s_nop 0
	global_load_lds_dwordx4 v186, s[22:23]
	s_add_i32 m0, s89, 0x2000
	s_nop 0
	global_load_lds_dwordx4 v190, s[22:23]
	s_waitcnt vmcnt(6)
	s_waitcnt lgkmcnt(0)
	v_mfma_f32_16x16x32_bf16 v[64:67], v[130:133], v[162:165], 0
	v_mfma_f32_16x16x32_bf16 v[68:71], v[138:141], v[162:165], 0
	s_barrier
	s_setprio 1
	s_waitcnt lgkmcnt(0)
	v_mfma_f32_16x16x32_bf16 v[82:85], v[130:133], v[170:173], 0
	v_mfma_f32_16x16x32_bf16 v[86:89], v[138:141], v[170:173], 0
	v_mfma_f32_16x16x32_bf16 v[98:101], v[130:133], v[178:181], 0
	v_mfma_f32_16x16x32_bf16 v[102:105], v[138:141], v[178:181], 0
	v_mfma_f32_16x16x32_bf16 v[114:117], v[130:133], v[202:205], 0
	v_mfma_f32_16x16x32_bf16 v[118:121], v[138:141], v[202:205], 0
	v_mfma_f32_16x16x32_bf16 v[64:67], v[134:137], v[166:169], v[64:67]
	v_mfma_f32_16x16x32_bf16 v[68:71], v[142:145], v[166:169], v[68:71]
	v_mfma_f32_16x16x32_bf16 v[82:85], v[134:137], v[174:177], v[82:85]
	v_mfma_f32_16x16x32_bf16 v[86:89], v[142:145], v[174:177], v[86:89]
	v_mfma_f32_16x16x32_bf16 v[98:101], v[134:137], v[198:201], v[98:101]
	v_mfma_f32_16x16x32_bf16 v[102:105], v[142:145], v[198:201], v[102:105]
	v_mfma_f32_16x16x32_bf16 v[114:117], v[134:137], v[206:209], v[114:117]
	v_mfma_f32_16x16x32_bf16 v[118:121], v[142:145], v[206:209], v[118:121]
	s_setprio 0
	s_setprio 1
	v_mfma_f32_16x16x32_bf16 v[76:79], v[146:149], v[162:165], 0
	v_mfma_f32_16x16x32_bf16 v[72:75], v[154:157], v[162:165], 0
	v_mfma_f32_16x16x32_bf16 v[94:97], v[146:149], v[170:173], 0
	v_mfma_f32_16x16x32_bf16 v[90:93], v[154:157], v[170:173], 0
	v_mfma_f32_16x16x32_bf16 v[110:113], v[146:149], v[178:181], 0
	v_mfma_f32_16x16x32_bf16 v[106:109], v[154:157], v[178:181], 0
	v_mfma_f32_16x16x32_bf16 v[126:129], v[146:149], v[202:205], 0
	v_mfma_f32_16x16x32_bf16 v[122:125], v[154:157], v[202:205], 0
	v_mfma_f32_16x16x32_bf16 v[76:79], v[150:153], v[166:169], v[76:79]
	v_mfma_f32_16x16x32_bf16 v[72:75], v[158:161], v[166:169], v[72:75]
	v_mfma_f32_16x16x32_bf16 v[94:97], v[150:153], v[174:177], v[94:97]
	v_mfma_f32_16x16x32_bf16 v[90:93], v[158:161], v[174:177], v[90:93]
	v_mfma_f32_16x16x32_bf16 v[110:113], v[150:153], v[198:201], v[110:113]
	v_mfma_f32_16x16x32_bf16 v[106:109], v[158:161], v[198:201], v[106:109]
	v_mfma_f32_16x16x32_bf16 v[126:129], v[150:153], v[206:209], v[126:129]
	v_mfma_f32_16x16x32_bf16 v[122:125], v[158:161], v[206:209], v[122:125]
	s_setprio 0
	s_barrier
; #define PG8_STAGE(bufoff, gbase, voff) do { _Pragma("unroll") for (int _i = 0; _i < 2; ++_i) \
;         __builtin_amdgcn_global_load_lds((const unsigned*)((const char*)(gbase) + (voff)[_i]), (PG8_LAS unsigned*)(lds + (bufoff) + ldsw + _i * 8192), 16, 0, 0); } while (0)
; #define PG8_LDA(dst, b, h) do { _Pragma("unroll") for (int m = 0; m < 4; ++m) _Pragma("unroll") for (int k = 0; k < 2; ++k) dst[m][k] = *(const PG8_LAS bf16x8*)(lds + PG8_SA(b, h) + aoff + m * 2048 + k * 1024); } while (0)
; #define PG8_LDB(dst, b, h) do { _Pragma("unroll") for (int n = 0; n < 2; ++n) _Pragma("unroll") for (int k = 0; k < 2; ++k) dst[n][k] = *(const PG8_LAS bf16x8*)(lds + PG8_SB(b, h) + boff + n * 2048 + k * 1024); } while (0)
; template <class Epi, class Sched, bool ALIGN_EPI = false>
; __device__ __forceinline__ void gemm_phase(PG8_LAS unsigned char* lds, const Gemm g, const Sched& S, const Epi& E, int tid_in) {
;     ...
;         for (int t = 0; t < nt; t += 2) {
;             const bool last = (t == nt - 2);
;             const char* a1 = cA + (size_t)(t + 1) * kstep;
;             const char* a2 = last ? nA : cA + (size_t)(t + 2) * kstep; const char* b2 = last ? nB : cB + (size_t)(t + 2) * kstep;
;             const char* a3 = a2 + kstep; const char* b3 = b2 + kstep;
;             if (last && has_next) S.a_ready(nxt);
;             E.mid(acc, cur, t, tid_, wr, wc);
;             PG8_LDB(B0, 0, 0); PG8_LDB(B1, 0, 1); PG8_SCHED; PG8_LDA(At, 0, 0); PG8_STAGE(PG8_SA(1, 1), a1 + hstepA, voffA);
;             PG8_WAIT_V(8); PG8_WAIT_L(0); PG8_BAR; PG8_MMA(0, 0, At, B0); PG8_MMA(0, 1, At, B1); PG8_BAR; PG8_SCHED;
;             PG8_LDA(At, 0, 1); PG8_STAGE(PG8_SB(0, 0), b2, voffB); PG8_STAGE(PG8_SB(0, 1), b2 + hstepB, voffB); PG8_STAGE(PG8_SA(0, 0), a2, voffA);
;             PG8_WAIT_V(8); PG8_WAIT_L(0); PG8_BAR; PG8_MMA(1, 0, At, B0); PG8_MMA(1, 1, At, B1); PG8_BAR; PG8_SCHED;
;             PG8_LDB(B0, 1, 0); PG8_LDB(B1, 1, 1); PG8_SCHED; PG8_LDA(At, 1, 0); PG8_STAGE(PG8_SA(0, 1), a2 + hstepA, voffA);
;             PG8_WAIT_V(8); PG8_WAIT_L(0); PG8_BAR; PG8_MMA(0, 0, At, B0); PG8_MMA(0, 1, At, B1); PG8_BAR; PG8_SCHED;
;             PG8_LDA(At, 1, 1); PG8_STAGE(PG8_SB(1, 0), b3, voffB); PG8_STAGE(PG8_SB(1, 1), b3 + hstepB, voffB); PG8_STAGE(PG8_SA(1, 0), a3, voffA);
;             PG8_WAIT_V(8); PG8_WAIT_L(0); PG8_BAR; PG8_MMA(1, 0, At, B0); PG8_MMA(1, 1, At, B1); PG8_BAR; PG8_SCHED;
	s_add_i32 s89, 0, 0x18000
	v_add_u32_e32 v80, s89, v245
	s_add_i32 s90, 0, 0x1c000
	ds_read_b128 v[130:133], v80
	ds_read_b128 v[134:137], v80 offset:1024
	ds_read_b128 v[138:141], v80 offset:2048
	ds_read_b128 v[142:145], v80 offset:3072
	v_add_u32_e32 v80, s90, v245
	ds_read_b128 v[146:149], v80
	ds_read_b128 v[150:153], v80 offset:1024
	ds_read_b128 v[154:157], v80 offset:2048
	ds_read_b128 v[158:161], v80 offset:3072
	s_add_u32 s22, s58, s0
	s_addc_u32 s23, s59, 0
	s_mov_b32 m0, s70
	ds_read_b128 v[162:165], v248 offset:32768
	ds_read_b128 v[166:169], v248 offset:33792
	ds_read_b128 v[170:173], v248 offset:34816
	ds_read_b128 v[174:177], v248 offset:35840
	ds_read_b128 v[178:181], v248 offset:36864
	ds_read_b128 v[198:201], v248 offset:37888
	ds_read_b128 v[202:205], v248 offset:38912
	ds_read_b128 v[206:209], v248 offset:39936
	global_load_lds_dwordx4 v184, s[58:59]
	s_mov_b32 m0, s71
	s_nop 0
	global_load_lds_dwordx4 v188, s[58:59]
	s_mov_b32 m0, s72
	s_nop 0
	global_load_lds_dwordx4 v184, s[22:23]
	s_mov_b32 m0, s73
	s_nop 0
	global_load_lds_dwordx4 v188, s[22:23]
	s_waitcnt vmcnt(8)
	s_waitcnt lgkmcnt(0)
	v_mfma_f32_16x16x32_bf16 v[4:7], v[130:133], v[162:165], v[4:7]
	v_mfma_f32_16x16x32_bf16 v[0:3], v[138:141], v[162:165], v[0:3]
	s_barrier
	s_setprio 1
	s_waitcnt lgkmcnt(0)
	v_mfma_f32_16x16x32_bf16 v[20:23], v[130:133], v[170:173], v[20:23]
	v_mfma_f32_16x16x32_bf16 v[16:19], v[138:141], v[170:173], v[16:19]
	v_mfma_f32_16x16x32_bf16 v[36:39], v[130:133], v[178:181], v[36:39]
	v_mfma_f32_16x16x32_bf16 v[32:35], v[138:141], v[178:181], v[32:35]
	v_mfma_f32_16x16x32_bf16 v[52:55], v[130:133], v[202:205], v[52:55]
	v_mfma_f32_16x16x32_bf16 v[48:51], v[138:141], v[202:205], v[48:51]
	v_mfma_f32_16x16x32_bf16 v[4:7], v[134:137], v[166:169], v[4:7]
	v_mfma_f32_16x16x32_bf16 v[0:3], v[142:145], v[166:169], v[0:3]
	v_mfma_f32_16x16x32_bf16 v[20:23], v[134:137], v[174:177], v[20:23]
	v_mfma_f32_16x16x32_bf16 v[16:19], v[142:145], v[174:177], v[16:19]
	v_mfma_f32_16x16x32_bf16 v[36:39], v[134:137], v[198:201], v[36:39]
	v_mfma_f32_16x16x32_bf16 v[32:35], v[142:145], v[198:201], v[32:35]
	v_mfma_f32_16x16x32_bf16 v[52:55], v[134:137], v[206:209], v[52:55]
	v_mfma_f32_16x16x32_bf16 v[48:51], v[142:145], v[206:209], v[48:51]
	s_setprio 0
	s_setprio 1
	v_mfma_f32_16x16x32_bf16 v[12:15], v[146:149], v[162:165], v[12:15]
	v_mfma_f32_16x16x32_bf16 v[8:11], v[154:157], v[162:165], v[8:11]
	v_mfma_f32_16x16x32_bf16 v[28:31], v[146:149], v[170:173], v[28:31]
	v_mfma_f32_16x16x32_bf16 v[24:27], v[154:157], v[170:173], v[24:27]
	v_mfma_f32_16x16x32_bf16 v[44:47], v[146:149], v[178:181], v[44:47]
	v_mfma_f32_16x16x32_bf16 v[40:43], v[154:157], v[178:181], v[40:43]
	v_mfma_f32_16x16x32_bf16 v[60:63], v[146:149], v[202:205], v[60:63]
	v_mfma_f32_16x16x32_bf16 v[56:59], v[154:157], v[202:205], v[56:59]
	v_mfma_f32_16x16x32_bf16 v[12:15], v[150:153], v[166:169], v[12:15]
	v_mfma_f32_16x16x32_bf16 v[8:11], v[158:161], v[166:169], v[8:11]
	v_mfma_f32_16x16x32_bf16 v[28:31], v[150:153], v[174:177], v[28:31]
	v_mfma_f32_16x16x32_bf16 v[24:27], v[158:161], v[174:177], v[24:27]
	v_mfma_f32_16x16x32_bf16 v[44:47], v[150:153], v[198:201], v[44:47]
	v_mfma_f32_16x16x32_bf16 v[40:43], v[158:161], v[198:201], v[40:43]
	v_mfma_f32_16x16x32_bf16 v[60:63], v[150:153], v[206:209], v[60:63]
	v_mfma_f32_16x16x32_bf16 v[56:59], v[158:161], v[206:209], v[56:59]
	s_setprio 0
	s_barrier
	s_add_i32 s22, s89, s69
	s_add_u32 vcc_lo, vcc_lo, 0x80
	s_addc_u32 vcc_hi, vcc_hi, 0
	s_mov_b32 m0, s22
	ds_read_b128 v[162:165], v248 offset:49152
	ds_read_b128 v[166:169], v248 offset:50176
	ds_read_b128 v[170:173], v248 offset:51200
	ds_read_b128 v[174:177], v248 offset:52224
	ds_read_b128 v[178:181], v248 offset:53248
	ds_read_b128 v[198:201], v248 offset:54272
	ds_read_b128 v[202:205], v248 offset:55296
	ds_read_b128 v[206:209], v248 offset:56320
	global_load_lds_dwordx4 v186, vcc
	s_add_i32 m0, s22, 0x2000
	s_add_i32 s22, s90, s69
	global_load_lds_dwordx4 v190, vcc
	s_add_u32 vcc_lo, vcc_lo, s33
	s_addc_u32 vcc_hi, vcc_hi, 0
	s_mov_b32 m0, s22
	s_nop 0
	global_load_lds_dwordx4 v186, vcc
	s_add_i32 m0, s22, 0x2000
	s_nop 0
	global_load_lds_dwordx4 v190, vcc
	s_waitcnt vmcnt(6)
	s_waitcnt lgkmcnt(0)
	v_mfma_f32_16x16x32_bf16 v[64:67], v[130:133], v[162:165], v[64:67]
	v_mfma_f32_16x16x32_bf16 v[68:71], v[138:141], v[162:165], v[68:71]
	s_barrier
	s_setprio 1
	s_waitcnt lgkmcnt(0)
	v_mfma_f32_16x16x32_bf16 v[82:85], v[130:133], v[170:173], v[82:85]
	v_mfma_f32_16x16x32_bf16 v[86:89], v[138:141], v[170:173], v[86:89]
	v_mfma_f32_16x16x32_bf16 v[98:101], v[130:133], v[178:181], v[98:101]
	v_mfma_f32_16x16x32_bf16 v[102:105], v[138:141], v[178:181], v[102:105]
	v_mfma_f32_16x16x32_bf16 v[114:117], v[130:133], v[202:205], v[114:117]
	v_mfma_f32_16x16x32_bf16 v[118:121], v[138:141], v[202:205], v[118:121]
	v_mfma_f32_16x16x32_bf16 v[64:67], v[134:137], v[166:169], v[64:67]
	v_mfma_f32_16x16x32_bf16 v[68:71], v[142:145], v[166:169], v[68:71]
	v_mfma_f32_16x16x32_bf16 v[82:85], v[134:137], v[174:177], v[82:85]
	v_mfma_f32_16x16x32_bf16 v[86:89], v[142:145], v[174:177], v[86:89]
	v_mfma_f32_16x16x32_bf16 v[98:101], v[134:137], v[198:201], v[98:101]
	v_mfma_f32_16x16x32_bf16 v[102:105], v[142:145], v[198:201], v[102:105]
	v_mfma_f32_16x16x32_bf16 v[114:117], v[134:137], v[206:209], v[114:117]
	v_mfma_f32_16x16x32_bf16 v[118:121], v[142:145], v[206:209], v[118:121]
	s_setprio 0
	s_setprio 1
	v_mfma_f32_16x16x32_bf16 v[76:79], v[146:149], v[162:165], v[76:79]
	v_mfma_f32_16x16x32_bf16 v[72:75], v[154:157], v[162:165], v[72:75]
	v_mfma_f32_16x16x32_bf16 v[94:97], v[146:149], v[170:173], v[94:97]
	v_mfma_f32_16x16x32_bf16 v[90:93], v[154:157], v[170:173], v[90:93]
	v_mfma_f32_16x16x32_bf16 v[110:113], v[146:149], v[178:181], v[110:113]
	v_mfma_f32_16x16x32_bf16 v[106:109], v[154:157], v[178:181], v[106:109]
	v_mfma_f32_16x16x32_bf16 v[126:129], v[146:149], v[202:205], v[126:129]
	v_mfma_f32_16x16x32_bf16 v[122:125], v[154:157], v[202:205], v[122:125]
	v_mfma_f32_16x16x32_bf16 v[76:79], v[150:153], v[166:169], v[76:79]
	v_mfma_f32_16x16x32_bf16 v[72:75], v[158:161], v[166:169], v[72:75]
	v_mfma_f32_16x16x32_bf16 v[94:97], v[150:153], v[174:177], v[94:97]
	v_mfma_f32_16x16x32_bf16 v[90:93], v[158:161], v[174:177], v[90:93]
	v_mfma_f32_16x16x32_bf16 v[110:113], v[150:153], v[198:201], v[110:113]
	v_mfma_f32_16x16x32_bf16 v[106:109], v[158:161], v[198:201], v[106:109]
	v_mfma_f32_16x16x32_bf16 v[126:129], v[150:153], v[206:209], v[126:129]
	v_mfma_f32_16x16x32_bf16 v[122:125], v[158:161], v[206:209], v[122:125]
	s_setprio 0
	s_barrier
	s_add_u32 s60, s60, 0x100
	s_addc_u32 s61, s61, 0
	s_add_u32 s57, s57, 0x100
	s_addc_u32 s62, s62, 0
	s_cmp_ge_u32 s63, s76
	s_mov_b32 s58, s63
	s_cbranch_scc0 .LBB0_267
	s_branch .Lkloop_exit
; #define PG8_STAGE(bufoff, gbase, voff) do { _Pragma("unroll") for (int _i = 0; _i < 2; ++_i) \
;         __builtin_amdgcn_global_load_lds((const unsigned*)((const char*)(gbase) + (voff)[_i]), (PG8_LAS unsigned*)(lds + (bufoff) + ldsw + _i * 8192), 16, 0, 0); } while (0)
; #define PG8_LDA(dst, b, h) do { _Pragma("unroll") for (int m = 0; m < 4; ++m) _Pragma("unroll") for (int k = 0; k < 2; ++k) dst[m][k] = *(const PG8_LAS bf16x8*)(lds + PG8_SA(b, h) + aoff + m * 2048 + k * 1024); } while (0)
; #define PG8_LDB(dst, b, h) do { _Pragma("unroll") for (int n = 0; n < 2; ++n) _Pragma("unroll") for (int k = 0; k < 2; ++k) dst[n][k] = *(const PG8_LAS bf16x8*)(lds + PG8_SB(b, h) + boff + n * 2048 + k * 1024); } while (0)
; #define PG8_MMA(ai, bj, At, Bt) do { __builtin_amdgcn_s_setprio(1); _Pragma("unroll") for (int m = 0; m < 4; ++m) _Pragma("unroll") for (int n = 0; n < 2; ++n) _Pragma("unroll") for (int k = 0; k < 2; ++k) \
;         acc[ai][bj][m][n] = __builtin_amdgcn_mfma_f32_16x16x32_bf16(Bt[n][k], At[m][k], acc[ai][bj][m][n], 0, 0, 0); __builtin_amdgcn_s_setprio(0); } while (0)
; #define PG8_WAIT_V(n) asm volatile("s_waitcnt vmcnt(" #n ")" ::: "memory")
; #define PG8_BAR __builtin_amdgcn_s_barrier()
; template <class Epi, class Sched, bool ALIGN_EPI = false>
; __device__ __forceinline__ void gemm_phase(PG8_LAS unsigned char* lds, const Gemm g, const Sched& S, const Epi& E, int tid_in) {
;     ...
;         for (int t = 0; t < nt; t += 2) {
;             const bool last = (t == nt - 2);
;             const char* a1 = cA + (size_t)(t + 1) * kstep;
;             const char* a2 = last ? nA : cA + (size_t)(t + 2) * kstep; const char* b2 = last ? nB : cB + (size_t)(t + 2) * kstep;
;             const char* a3 = a2 + kstep; const char* b3 = b2 + kstep;
;             if (last && has_next) S.a_ready(nxt);
;             E.mid(acc, cur, t, tid_, wr, wc);
;             PG8_LDB(B0, 0, 0); PG8_LDB(B1, 0, 1); PG8_SCHED; PG8_LDA(At, 0, 0); PG8_STAGE(PG8_SA(1, 1), a1 + hstepA, voffA);
;             PG8_WAIT_V(8); PG8_WAIT_L(0); PG8_BAR; PG8_MMA(0, 0, At, B0); PG8_MMA(0, 1, At, B1); PG8_BAR; PG8_SCHED;
;             PG8_LDA(At, 0, 1); PG8_STAGE(PG8_SB(0, 0), b2, voffB); PG8_STAGE(PG8_SB(0, 1), b2 + hstepB, voffB); PG8_STAGE(PG8_SA(0, 0), a2, voffA);
;             PG8_WAIT_V(8); PG8_WAIT_L(0); PG8_BAR; PG8_MMA(1, 0, At, B0); PG8_MMA(1, 1, At, B1); PG8_BAR; PG8_SCHED;
.Lk_nopeel:
	s_waitcnt vmcnt(0)
.LBB0_267:
	s_add_i32 s63, s58, 2
	s_add_u32 s22, s60, 0x80
	s_addc_u32 s23, s61, 0
	s_add_i32 s89, 0, 0x10000
	s_cmp_eq_u32 s77, s58
	s_cselect_b32 s59, s19, s23
	s_cselect_b32 s58, s18, s22
	v_add_u32_e32 v80, s89, v245
	s_cselect_b32 s23, s35, s62
	s_cselect_b32 s22, s34, s57
	s_add_i32 s90, 0, 0x14000
	ds_read_b128 v[130:133], v80
	ds_read_b128 v[134:137], v80 offset:1024
	ds_read_b128 v[138:141], v80 offset:2048
	ds_read_b128 v[142:145], v80 offset:3072
	v_add_u32_e32 v80, s90, v245
	ds_read_b128 v[146:149], v80
	ds_read_b128 v[150:153], v80 offset:1024
	ds_read_b128 v[154:157], v80 offset:2048
	ds_read_b128 v[158:161], v80 offset:3072
	s_mov_b32 m0, s74
	ds_read_b128 v[162:165], v248
	ds_read_b128 v[166:169], v248 offset:1024
	ds_read_b128 v[170:173], v248 offset:2048
	ds_read_b128 v[174:177], v248 offset:3072
	ds_read_b128 v[178:181], v248 offset:4096
	ds_read_b128 v[198:201], v248 offset:5120
	ds_read_b128 v[202:205], v248 offset:6144
	ds_read_b128 v[206:209], v248 offset:7168
	global_load_lds_dwordx4 v184, s[60:61]
	s_mov_b32 m0, s75
	s_nop 0
	global_load_lds_dwordx4 v188, s[60:61]
	s_add_i32 m0, s70, 0xc000
	s_nop 0
	global_load_lds_dwordx4 v194, s[60:61]
	s_add_i32 m0, s70, 0xe000
	s_nop 0
	global_load_lds_dwordx4 v196, s[60:61]
	s_waitcnt vmcnt(8)
	s_waitcnt lgkmcnt(0)
	v_mfma_f32_16x16x32_bf16 v[4:7], v[130:133], v[162:165], v[4:7]
	v_mfma_f32_16x16x32_bf16 v[0:3], v[138:141], v[162:165], v[0:3]
	s_barrier
	s_setprio 1
	s_waitcnt lgkmcnt(0)
	v_mfma_f32_16x16x32_bf16 v[20:23], v[130:133], v[170:173], v[20:23]
	v_mfma_f32_16x16x32_bf16 v[16:19], v[138:141], v[170:173], v[16:19]
	v_mfma_f32_16x16x32_bf16 v[36:39], v[130:133], v[178:181], v[36:39]
	v_mfma_f32_16x16x32_bf16 v[32:35], v[138:141], v[178:181], v[32:35]
	v_mfma_f32_16x16x32_bf16 v[52:55], v[130:133], v[202:205], v[52:55]
	v_mfma_f32_16x16x32_bf16 v[48:51], v[138:141], v[202:205], v[48:51]
	v_mfma_f32_16x16x32_bf16 v[4:7], v[134:137], v[166:169], v[4:7]
	v_mfma_f32_16x16x32_bf16 v[0:3], v[142:145], v[166:169], v[0:3]
	v_mfma_f32_16x16x32_bf16 v[20:23], v[134:137], v[174:177], v[20:23]
	v_mfma_f32_16x16x32_bf16 v[16:19], v[142:145], v[174:177], v[16:19]
	v_mfma_f32_16x16x32_bf16 v[36:39], v[134:137], v[198:201], v[36:39]
	v_mfma_f32_16x16x32_bf16 v[32:35], v[142:145], v[198:201], v[32:35]
	v_mfma_f32_16x16x32_bf16 v[52:55], v[134:137], v[206:209], v[52:55]
	v_mfma_f32_16x16x32_bf16 v[48:51], v[142:145], v[206:209], v[48:51]
	s_setprio 0
	s_setprio 1
	v_mfma_f32_16x16x32_bf16 v[12:15], v[146:149], v[162:165], v[12:15]
	v_mfma_f32_16x16x32_bf16 v[8:11], v[154:157], v[162:165], v[8:11]
	v_mfma_f32_16x16x32_bf16 v[28:31], v[146:149], v[170:173], v[28:31]
	v_mfma_f32_16x16x32_bf16 v[24:27], v[154:157], v[170:173], v[24:27]
	v_mfma_f32_16x16x32_bf16 v[44:47], v[146:149], v[178:181], v[44:47]
	v_mfma_f32_16x16x32_bf16 v[40:43], v[154:157], v[178:181], v[40:43]
	v_mfma_f32_16x16x32_bf16 v[60:63], v[146:149], v[202:205], v[60:63]
	v_mfma_f32_16x16x32_bf16 v[56:59], v[154:157], v[202:205], v[56:59]
	v_mfma_f32_16x16x32_bf16 v[12:15], v[150:153], v[166:169], v[12:15]
	v_mfma_f32_16x16x32_bf16 v[8:11], v[158:161], v[166:169], v[8:11]
	v_mfma_f32_16x16x32_bf16 v[28:31], v[150:153], v[174:177], v[28:31]
	v_mfma_f32_16x16x32_bf16 v[24:27], v[158:161], v[174:177], v[24:27]
	v_mfma_f32_16x16x32_bf16 v[44:47], v[150:153], v[198:201], v[44:47]
	v_mfma_f32_16x16x32_bf16 v[40:43], v[158:161], v[198:201], v[40:43]
	v_mfma_f32_16x16x32_bf16 v[60:63], v[150:153], v[206:209], v[60:63]
	v_mfma_f32_16x16x32_bf16 v[56:59], v[158:161], v[206:209], v[56:59]
	s_setprio 0
	s_barrier
	s_add_i32 s89, s89, s69
	s_mov_b64 vcc, s[22:23]
	s_mov_b32 m0, s89
	ds_read_b128 v[162:165], v248 offset:16384
	ds_read_b128 v[166:169], v248 offset:17408
	ds_read_b128 v[170:173], v248 offset:18432
	ds_read_b128 v[174:177], v248 offset:19456
	ds_read_b128 v[178:181], v248 offset:20480
	ds_read_b128 v[198:201], v248 offset:21504
	ds_read_b128 v[202:205], v248 offset:22528
	ds_read_b128 v[206:209], v248 offset:23552
	global_load_lds_dwordx4 v186, s[22:23]
	s_add_i32 m0, s89, 0x2000
	s_add_u32 s22, s22, s33
	s_addc_u32 s23, s23, 0
	s_add_i32 s89, s90, s69
	global_load_lds_dwordx4 v190, vcc
	s_mov_b32 m0, s89
	s_nop 0
	global_load_lds_dwordx4 v186, s[22:23]
	s_add_i32 m0, s89, 0x2000
	s_nop 0
	global_load_lds_dwordx4 v190, s[22:23]
	s_waitcnt vmcnt(6)
	s_waitcnt lgkmcnt(0)
	v_mfma_f32_16x16x32_bf16 v[64:67], v[130:133], v[162:165], v[64:67]
	v_mfma_f32_16x16x32_bf16 v[68:71], v[138:141], v[162:165], v[68:71]
	s_barrier
; #define PG8_STAGE(bufoff, gbase, voff) do { _Pragma("unroll") for (int _i = 0; _i < 2; ++_i) \
;         __builtin_amdgcn_global_load_lds((const unsigned*)((const char*)(gbase) + (voff)[_i]), (PG8_LAS unsigned*)(lds + (bufoff) + ldsw + _i * 8192), 16, 0, 0); } while (0)
; #define PG8_LDA(dst, b, h) do { _Pragma("unroll") for (int m = 0; m < 4; ++m) _Pragma("unroll") for (int k = 0; k < 2; ++k) dst[m][k] = *(const PG8_LAS bf16x8*)(lds + PG8_SA(b, h) + aoff + m * 2048 + k * 1024); } while (0)
; #define PG8_LDB(dst, b, h) do { _Pragma("unroll") for (int n = 0; n < 2; ++n) _Pragma("unroll") for (int k = 0; k < 2; ++k) dst[n][k] = *(const PG8_LAS bf16x8*)(lds + PG8_SB(b, h) + boff + n * 2048 + k * 1024); } while (0)
; #define PG8_MMA(ai, bj, At, Bt) do { __builtin_amdgcn_s_setprio(1); _Pragma("unroll") for (int m = 0; m < 4; ++m) _Pragma("unroll") for (int n = 0; n < 2; ++n) _Pragma("unroll") for (int k = 0; k < 2; ++k) \
;         acc[ai][bj][m][n] = __builtin_amdgcn_mfma_f32_16x16x32_bf16(Bt[n][k], At[m][k], acc[ai][bj][m][n], 0, 0, 0); __builtin_amdgcn_s_setprio(0); } while (0)
; #define PG8_WAIT_V(n) asm volatile("s_waitcnt vmcnt(" #n ")" ::: "memory")
; #define PG8_WAIT_L(n) asm volatile("s_waitcnt lgkmcnt(" #n ")" ::: "memory")
; #define PG8_BAR __builtin_amdgcn_s_barrier()
; #define PG8_SCHED __builtin_amdgcn_sched_barrier(0)
; template <class Epi, class Sched, bool ALIGN_EPI = false>
; __device__ __forceinline__ void gemm_phase(PG8_LAS unsigned char* lds, const Gemm g, const Sched& S, const Epi& E, int tid_in) {
;     ...
;             PG8_WAIT_V(8); PG8_WAIT_L(0); PG8_BAR; PG8_MMA(1, 0, At, B0); PG8_MMA(1, 1, At, B1); PG8_BAR; PG8_SCHED;
;             PG8_LDB(B0, 1, 0); PG8_LDB(B1, 1, 1); PG8_SCHED; PG8_LDA(At, 1, 0); PG8_STAGE(PG8_SA(0, 1), a2 + hstepA, voffA);
;             PG8_WAIT_V(8); PG8_WAIT_L(0); PG8_BAR; PG8_MMA(0, 0, At, B0); PG8_MMA(0, 1, At, B1); PG8_BAR; PG8_SCHED;
	s_setprio 1
	s_waitcnt lgkmcnt(0)
	v_mfma_f32_16x16x32_bf16 v[82:85], v[130:133], v[170:173], v[82:85]
	v_mfma_f32_16x16x32_bf16 v[86:89], v[138:141], v[170:173], v[86:89]
	v_mfma_f32_16x16x32_bf16 v[98:101], v[130:133], v[178:181], v[98:101]
	v_mfma_f32_16x16x32_bf16 v[102:105], v[138:141], v[178:181], v[102:105]
	v_mfma_f32_16x16x32_bf16 v[114:117], v[130:133], v[202:205], v[114:117]
	v_mfma_f32_16x16x32_bf16 v[118:121], v[138:141], v[202:205], v[118:121]
	v_mfma_f32_16x16x32_bf16 v[64:67], v[134:137], v[166:169], v[64:67]
	v_mfma_f32_16x16x32_bf16 v[68:71], v[142:145], v[166:169], v[68:71]
	v_mfma_f32_16x16x32_bf16 v[82:85], v[134:137], v[174:177], v[82:85]
	v_mfma_f32_16x16x32_bf16 v[86:89], v[142:145], v[174:177], v[86:89]
	v_mfma_f32_16x16x32_bf16 v[98:101], v[134:137], v[198:201], v[98:101]
	v_mfma_f32_16x16x32_bf16 v[102:105], v[142:145], v[198:201], v[102:105]
	v_mfma_f32_16x16x32_bf16 v[114:117], v[134:137], v[206:209], v[114:117]
	v_mfma_f32_16x16x32_bf16 v[118:121], v[142:145], v[206:209], v[118:121]
	s_setprio 0
	s_setprio 1
	v_mfma_f32_16x16x32_bf16 v[76:79], v[146:149], v[162:165], v[76:79]
	v_mfma_f32_16x16x32_bf16 v[72:75], v[154:157], v[162:165], v[72:75]
	v_mfma_f32_16x16x32_bf16 v[94:97], v[146:149], v[170:173], v[94:97]
	v_mfma_f32_16x16x32_bf16 v[90:93], v[154:157], v[170:173], v[90:93]
	v_mfma_f32_16x16x32_bf16 v[110:113], v[146:149], v[178:181], v[110:113]
	v_mfma_f32_16x16x32_bf16 v[106:109], v[154:157], v[178:181], v[106:109]
	v_mfma_f32_16x16x32_bf16 v[126:129], v[146:149], v[202:205], v[126:129]
	v_mfma_f32_16x16x32_bf16 v[122:125], v[154:157], v[202:205], v[122:125]
	v_mfma_f32_16x16x32_bf16 v[76:79], v[150:153], v[166:169], v[76:79]
	v_mfma_f32_16x16x32_bf16 v[72:75], v[158:161], v[166:169], v[72:75]
	v_mfma_f32_16x16x32_bf16 v[94:97], v[150:153], v[174:177], v[94:97]
	v_mfma_f32_16x16x32_bf16 v[90:93], v[158:161], v[174:177], v[90:93]
	v_mfma_f32_16x16x32_bf16 v[110:113], v[150:153], v[198:201], v[110:113]
	v_mfma_f32_16x16x32_bf16 v[106:109], v[158:161], v[198:201], v[106:109]
	v_mfma_f32_16x16x32_bf16 v[126:129], v[150:153], v[206:209], v[126:129]
	v_mfma_f32_16x16x32_bf16 v[122:125], v[158:161], v[206:209], v[122:125]
	s_setprio 0
	s_barrier
	s_add_i32 s89, 0, 0x18000
	v_add_u32_e32 v80, s89, v245
	s_add_i32 s90, 0, 0x1c000
	ds_read_b128 v[130:133], v80
	ds_read_b128 v[134:137], v80 offset:1024
	ds_read_b128 v[138:141], v80 offset:2048
	ds_read_b128 v[142:145], v80 offset:3072
	v_add_u32_e32 v80, s90, v245
	ds_read_b128 v[146:149], v80
	ds_read_b128 v[150:153], v80 offset:1024
	ds_read_b128 v[154:157], v80 offset:2048
	ds_read_b128 v[158:161], v80 offset:3072
	s_add_u32 s22, s58, s0
	s_addc_u32 s23, s59, 0
	s_mov_b32 m0, s70
	ds_read_b128 v[162:165], v248 offset:32768
	ds_read_b128 v[166:169], v248 offset:33792
	ds_read_b128 v[170:173], v248 offset:34816
	ds_read_b128 v[174:177], v248 offset:35840
	ds_read_b128 v[178:181], v248 offset:36864
	ds_read_b128 v[198:201], v248 offset:37888
	ds_read_b128 v[202:205], v248 offset:38912
	ds_read_b128 v[206:209], v248 offset:39936
	global_load_lds_dwordx4 v184, s[58:59]
	s_mov_b32 m0, s71
	s_nop 0
	global_load_lds_dwordx4 v188, s[58:59]
	s_mov_b32 m0, s72
	s_nop 0
	global_load_lds_dwordx4 v184, s[22:23]
	s_mov_b32 m0, s73
	s_nop 0
	global_load_lds_dwordx4 v188, s[22:23]
	s_waitcnt vmcnt(8)
	s_waitcnt lgkmcnt(0)
	v_mfma_f32_16x16x32_bf16 v[4:7], v[130:133], v[162:165], v[4:7]
	v_mfma_f32_16x16x32_bf16 v[0:3], v[138:141], v[162:165], v[0:3]
	s_barrier
	s_setprio 1
	s_waitcnt lgkmcnt(0)
	v_mfma_f32_16x16x32_bf16 v[20:23], v[130:133], v[170:173], v[20:23]
	v_mfma_f32_16x16x32_bf16 v[16:19], v[138:141], v[170:173], v[16:19]
	v_mfma_f32_16x16x32_bf16 v[36:39], v[130:133], v[178:181], v[36:39]
	v_mfma_f32_16x16x32_bf16 v[32:35], v[138:141], v[178:181], v[32:35]
	v_mfma_f32_16x16x32_bf16 v[52:55], v[130:133], v[202:205], v[52:55]
	v_mfma_f32_16x16x32_bf16 v[48:51], v[138:141], v[202:205], v[48:51]
	v_mfma_f32_16x16x32_bf16 v[4:7], v[134:137], v[166:169], v[4:7]
	v_mfma_f32_16x16x32_bf16 v[0:3], v[142:145], v[166:169], v[0:3]
	v_mfma_f32_16x16x32_bf16 v[20:23], v[134:137], v[174:177], v[20:23]
	v_mfma_f32_16x16x32_bf16 v[16:19], v[142:145], v[174:177], v[16:19]
	v_mfma_f32_16x16x32_bf16 v[36:39], v[134:137], v[198:201], v[36:39]
	v_mfma_f32_16x16x32_bf16 v[32:35], v[142:145], v[198:201], v[32:35]
	v_mfma_f32_16x16x32_bf16 v[52:55], v[134:137], v[206:209], v[52:55]
	v_mfma_f32_16x16x32_bf16 v[48:51], v[142:145], v[206:209], v[48:51]
	s_setprio 0
	s_setprio 1
	v_mfma_f32_16x16x32_bf16 v[12:15], v[146:149], v[162:165], v[12:15]
	v_mfma_f32_16x16x32_bf16 v[8:11], v[154:157], v[162:165], v[8:11]
	v_mfma_f32_16x16x32_bf16 v[28:31], v[146:149], v[170:173], v[28:31]
	v_mfma_f32_16x16x32_bf16 v[24:27], v[154:157], v[170:173], v[24:27]
	v_mfma_f32_16x16x32_bf16 v[44:47], v[146:149], v[178:181], v[44:47]
	v_mfma_f32_16x16x32_bf16 v[40:43], v[154:157], v[178:181], v[40:43]
	v_mfma_f32_16x16x32_bf16 v[60:63], v[146:149], v[202:205], v[60:63]
	v_mfma_f32_16x16x32_bf16 v[56:59], v[154:157], v[202:205], v[56:59]
	v_mfma_f32_16x16x32_bf16 v[12:15], v[150:153], v[166:169], v[12:15]
	v_mfma_f32_16x16x32_bf16 v[8:11], v[158:161], v[166:169], v[8:11]
	v_mfma_f32_16x16x32_bf16 v[28:31], v[150:153], v[174:177], v[28:31]
	v_mfma_f32_16x16x32_bf16 v[24:27], v[158:161], v[174:177], v[24:27]
	v_mfma_f32_16x16x32_bf16 v[44:47], v[150:153], v[198:201], v[44:47]
	v_mfma_f32_16x16x32_bf16 v[40:43], v[158:161], v[198:201], v[40:43]
	v_mfma_f32_16x16x32_bf16 v[60:63], v[150:153], v[206:209], v[60:63]
	v_mfma_f32_16x16x32_bf16 v[56:59], v[158:161], v[206:209], v[56:59]
	s_setprio 0
	s_barrier
; #define PG8_STAGE(bufoff, gbase, voff) do { _Pragma("unroll") for (int _i = 0; _i < 2; ++_i) \
;         __builtin_amdgcn_global_load_lds((const unsigned*)((const char*)(gbase) + (voff)[_i]), (PG8_LAS unsigned*)(lds + (bufoff) + ldsw + _i * 8192), 16, 0, 0); } while (0)
; #define PG8_LDA(dst, b, h) do { _Pragma("unroll") for (int m = 0; m < 4; ++m) _Pragma("unroll") for (int k = 0; k < 2; ++k) dst[m][k] = *(const PG8_LAS bf16x8*)(lds + PG8_SA(b, h) + aoff + m * 2048 + k * 1024); } while (0)
; #define PG8_MMA(ai, bj, At, Bt) do { __builtin_amdgcn_s_setprio(1); _Pragma("unroll") for (int m = 0; m < 4; ++m) _Pragma("unroll") for (int n = 0; n < 2; ++n) _Pragma("unroll") for (int k = 0; k < 2; ++k) \
;         acc[ai][bj][m][n] = __builtin_amdgcn_mfma_f32_16x16x32_bf16(Bt[n][k], At[m][k], acc[ai][bj][m][n], 0, 0, 0); __builtin_amdgcn_s_setprio(0); } while (0)
; #define PG8_WAIT_V(n) asm volatile("s_waitcnt vmcnt(" #n ")" ::: "memory")
; #define PG8_WAIT_L(n) asm volatile("s_waitcnt lgkmcnt(" #n ")" ::: "memory")
; #define PG8_BAR __builtin_amdgcn_s_barrier()
; #define PG8_SCHED __builtin_amdgcn_sched_barrier(0)
; template <class Epi, class Sched, bool ALIGN_EPI = false>
; __device__ __forceinline__ void gemm_phase(PG8_LAS unsigned char* lds, const Gemm g, const Sched& S, const Epi& E, int tid_in) {
;     ...
;             PG8_LDA(At, 1, 1); PG8_STAGE(PG8_SB(1, 0), b3, voffB); PG8_STAGE(PG8_SB(1, 1), b3 + hstepB, voffB); PG8_STAGE(PG8_SA(1, 0), a3, voffA);
;             PG8_WAIT_V(8); PG8_WAIT_L(0); PG8_BAR; PG8_MMA(1, 0, At, B0); PG8_MMA(1, 1, At, B1); PG8_BAR; PG8_SCHED;
;         }
;         if constexpr (ALIGN_EPI) { if (wr == 0) PG8_BAR; }
;         E(acc, cur, wr, wc, fr, fq); S.done(cur);
	s_add_i32 s22, s89, s69
	s_add_u32 vcc_lo, vcc_lo, 0x80
	s_addc_u32 vcc_hi, vcc_hi, 0
	s_mov_b32 m0, s22
	ds_read_b128 v[162:165], v248 offset:49152
	ds_read_b128 v[166:169], v248 offset:50176
	ds_read_b128 v[170:173], v248 offset:51200
	ds_read_b128 v[174:177], v248 offset:52224
	ds_read_b128 v[178:181], v248 offset:53248
	ds_read_b128 v[198:201], v248 offset:54272
	ds_read_b128 v[202:205], v248 offset:55296
	ds_read_b128 v[206:209], v248 offset:56320
	global_load_lds_dwordx4 v186, vcc
	s_add_i32 m0, s22, 0x2000
	s_add_i32 s22, s90, s69
	global_load_lds_dwordx4 v190, vcc
	s_add_u32 vcc_lo, vcc_lo, s33
	s_addc_u32 vcc_hi, vcc_hi, 0
	s_mov_b32 m0, s22
	s_nop 0
	global_load_lds_dwordx4 v186, vcc
	s_add_i32 m0, s22, 0x2000
	s_nop 0
	global_load_lds_dwordx4 v190, vcc
	s_waitcnt vmcnt(6)
	s_waitcnt lgkmcnt(0)
	v_mfma_f32_16x16x32_bf16 v[64:67], v[130:133], v[162:165], v[64:67]
	v_mfma_f32_16x16x32_bf16 v[68:71], v[138:141], v[162:165], v[68:71]
	s_barrier
	s_setprio 1
	s_waitcnt lgkmcnt(0)
	v_mfma_f32_16x16x32_bf16 v[82:85], v[130:133], v[170:173], v[82:85]
	v_mfma_f32_16x16x32_bf16 v[86:89], v[138:141], v[170:173], v[86:89]
	v_mfma_f32_16x16x32_bf16 v[98:101], v[130:133], v[178:181], v[98:101]
	v_mfma_f32_16x16x32_bf16 v[102:105], v[138:141], v[178:181], v[102:105]
	v_mfma_f32_16x16x32_bf16 v[114:117], v[130:133], v[202:205], v[114:117]
	v_mfma_f32_16x16x32_bf16 v[118:121], v[138:141], v[202:205], v[118:121]
	v_mfma_f32_16x16x32_bf16 v[64:67], v[134:137], v[166:169], v[64:67]
	v_mfma_f32_16x16x32_bf16 v[68:71], v[142:145], v[166:169], v[68:71]
	v_mfma_f32_16x16x32_bf16 v[82:85], v[134:137], v[174:177], v[82:85]
	v_mfma_f32_16x16x32_bf16 v[86:89], v[142:145], v[174:177], v[86:89]
	v_mfma_f32_16x16x32_bf16 v[98:101], v[134:137], v[198:201], v[98:101]
	v_mfma_f32_16x16x32_bf16 v[102:105], v[142:145], v[198:201], v[102:105]
	v_mfma_f32_16x16x32_bf16 v[114:117], v[134:137], v[206:209], v[114:117]
	v_mfma_f32_16x16x32_bf16 v[118:121], v[142:145], v[206:209], v[118:121]
	s_setprio 0
	s_setprio 1
	v_mfma_f32_16x16x32_bf16 v[76:79], v[146:149], v[162:165], v[76:79]
	v_mfma_f32_16x16x32_bf16 v[72:75], v[154:157], v[162:165], v[72:75]
	v_mfma_f32_16x16x32_bf16 v[94:97], v[146:149], v[170:173], v[94:97]
	v_mfma_f32_16x16x32_bf16 v[90:93], v[154:157], v[170:173], v[90:93]
	v_mfma_f32_16x16x32_bf16 v[110:113], v[146:149], v[178:181], v[110:113]
	v_mfma_f32_16x16x32_bf16 v[106:109], v[154:157], v[178:181], v[106:109]
	v_mfma_f32_16x16x32_bf16 v[126:129], v[146:149], v[202:205], v[126:129]
	v_mfma_f32_16x16x32_bf16 v[122:125], v[154:157], v[202:205], v[122:125]
	v_mfma_f32_16x16x32_bf16 v[76:79], v[150:153], v[166:169], v[76:79]
	v_mfma_f32_16x16x32_bf16 v[72:75], v[158:161], v[166:169], v[72:75]
	v_mfma_f32_16x16x32_bf16 v[94:97], v[150:153], v[174:177], v[94:97]
	v_mfma_f32_16x16x32_bf16 v[90:93], v[158:161], v[174:177], v[90:93]
	v_mfma_f32_16x16x32_bf16 v[110:113], v[150:153], v[198:201], v[110:113]
	v_mfma_f32_16x16x32_bf16 v[106:109], v[158:161], v[198:201], v[106:109]
	v_mfma_f32_16x16x32_bf16 v[126:129], v[150:153], v[206:209], v[126:129]
	v_mfma_f32_16x16x32_bf16 v[122:125], v[158:161], v[206:209], v[122:125]
	s_setprio 0
	s_barrier
	s_add_u32 s60, s60, 0x100
	s_addc_u32 s61, s61, 0
	s_add_u32 s57, s57, 0x100
	s_addc_u32 s62, s62, 0
	s_cmp_ge_u32 s63, s76
	s_mov_b32 s58, s63
	s_cbranch_scc0 .LBB0_267
.Lkloop_exit:
	s_and_b64 vcc, exec, s[14:15]
	s_cbranch_vccnz .LBB0_271
	s_cmp_lt_i32 s64, 3
	s_mov_b64 s[58:59], -1
	s_cbranch_scc0 .LBB0_272

; __device__ __forceinline__ void res_init(const float* base, bool bf, f32x4 (&acc)[2][2][4][2], const Unit& u, int wr, int wc, int fr, int fq) {
;         const int row0 = u.pm * BM + wr * 64 + fr, col0 = u.pn * BM + wc * 32 + 8 * fq;
;         if (!bf) {
; #pragma unroll
;             for (int ai = 0; ai < 2; ++ai)
; #pragma unroll
;                 for (int m = 0; m < 4; ++m) { const size_t off = (size_t)(row0 + ai * HALF + m * 16) * 1024 + col0;
; #pragma unroll
;                     for (int bj = 0; bj < 2; ++bj)
; #pragma unroll
;                         for (int n = 0; n < 2; ++n) acc[ai][bj][m][n] = *(const f32x4*)(base + off + bj * HALF + n * 4); }
;     __device__ __forceinline__ void init(f32x4 (&acc)[2][2][4][2], const Unit& u, int wr, int wc, int fr, int fq) const {
;         if (kind == 2) res_init(base, (gi >> 2) != 0, acc, u, wr, wc, fr, fq);
;         else {
; #pragma unroll
;             for (int a = 0; a < 2; ++a)
; #pragma unroll
;                 for (int b = 0; b < 2; ++b)
; #pragma unroll
;                     for (int m = 0; m < 4; ++m)
; #pragma unroll
;                         for (int n = 0; n < 2; ++n) acc[a][b][m][n] = (f32x4){0.f, 0.f, 0.f, 0.f}; }
;     }
.LBB0_373:
	s_and_b64 vcc, exec, s[48:49]
	s_mov_b64 s[48:49], -1
	s_cbranch_vccnz .LBB0_256
	s_and_b64 vcc, exec, s[40:41]
	s_cbranch_vccnz .LBB0_379
	v_lshl_add_u32 v134, s1, 8, v244
	v_lshl_or_b32 v136, s86, 8, v247
	v_ashrrev_i32_e32 v137, 31, v136
	v_ashrrev_i32_e32 v135, 31, v134
	s_andn2_b64 vcc, exec, s[54:55]
	v_or_b32_e32 v138, 16, v134
	v_or_b32_e32 v132, 32, v134
	v_or_b32_e32 v130, 48, v134
	s_cbranch_vccnz .LBB0_377
	v_readlane_b32 s22, v254, 0
	v_readlane_b32 s23, v254, 1
	v_lshlrev_b64 v[0:1], 12, v[134:135]
	v_ashrrev_i32_e32 v139, 31, v138
	v_lshl_add_u64 v[48:49], v[136:137], 2, s[22:23]
	v_lshl_add_u64 v[114:115], v[48:49], 0, v[0:1]
	s_mov_b64 s[22:23], 0x80000
	v_lshl_add_u64 v[76:77], v[114:115], 0, s[22:23]
	s_mov_b32 s22, 0x80000
	v_add_co_u32_e32 v64, vcc, s22, v114
	s_mov_b64 s[22:23], 0x90000
	s_nop 0
	v_addc_co_u32_e32 v65, vcc, 0, v115, vcc
	v_lshl_add_u64 v[94:95], v[114:115], 0, s[22:23]
	s_mov_b32 s22, 0x90000
	v_add_co_u32_e32 v82, vcc, s22, v114
	s_mov_b64 s[22:23], 0xa0000
	s_nop 0
	v_addc_co_u32_e32 v83, vcc, 0, v115, vcc
	v_lshl_add_u64 v[110:111], v[114:115], 0, s[22:23]
	s_mov_b32 s22, 0xa0000
	v_add_co_u32_e32 v98, vcc, s22, v114
	s_mov_b64 s[22:23], 0xb0000
	v_ashrrev_i32_e32 v133, 31, v132
	v_ashrrev_i32_e32 v131, 31, v130
	v_addc_co_u32_e32 v99, vcc, 0, v115, vcc
	v_lshl_add_u64 v[126:127], v[114:115], 0, s[22:23]
	s_mov_b32 s22, 0xb0000
	global_load_dwordx4 v[0:3], v[114:115], off offset:16
	global_load_dwordx4 v[4:7], v[114:115], off
	global_load_dwordx4 v[8:11], v[114:115], off offset:528
	global_load_dwordx4 v[12:15], v[114:115], off offset:512
	v_lshlrev_b64 v[16:17], 12, v[138:139]
	v_lshlrev_b64 v[32:33], 12, v[132:133]
	v_lshlrev_b64 v[50:51], 12, v[130:131]
	v_add_co_u32_e32 v114, vcc, s22, v114
	v_lshl_add_u64 v[28:29], v[48:49], 0, v[16:17]
	v_lshl_add_u64 v[44:45], v[48:49], 0, v[32:33]
	v_lshl_add_u64 v[60:61], v[48:49], 0, v[50:51]
	v_addc_co_u32_e32 v115, vcc, 0, v115, vcc
	global_load_dwordx4 v[16:19], v[28:29], off offset:16
	global_load_dwordx4 v[20:23], v[28:29], off
	global_load_dwordx4 v[24:27], v[28:29], off offset:528
	s_nop 0
	global_load_dwordx4 v[28:31], v[28:29], off offset:512
	s_nop 0
	global_load_dwordx4 v[32:35], v[44:45], off offset:16
	global_load_dwordx4 v[36:39], v[44:45], off
	global_load_dwordx4 v[40:43], v[44:45], off offset:528
	s_nop 0
	global_load_dwordx4 v[44:47], v[44:45], off offset:512
	s_nop 0
	global_load_dwordx4 v[48:51], v[60:61], off offset:16
	global_load_dwordx4 v[52:55], v[60:61], off
	global_load_dwordx4 v[56:59], v[60:61], off offset:528
	s_nop 0
	global_load_dwordx4 v[60:63], v[60:61], off offset:512
	s_nop 0
	global_load_dwordx4 v[64:67], v[64:65], off
	s_nop 0
	global_load_dwordx4 v[72:75], v[76:77], off offset:528
	global_load_dwordx4 v[68:71], v[76:77], off offset:16
	s_nop 0
	global_load_dwordx4 v[76:79], v[76:77], off offset:512
	s_nop 0
	global_load_dwordx4 v[82:85], v[82:83], off
	s_nop 0
	global_load_dwordx4 v[90:93], v[94:95], off offset:528
	global_load_dwordx4 v[86:89], v[94:95], off offset:16
	s_nop 0
	global_load_dwordx4 v[94:97], v[94:95], off offset:512
	s_nop 0
	global_load_dwordx4 v[98:101], v[98:99], off
	s_nop 0
	global_load_dwordx4 v[106:109], v[110:111], off offset:528
	global_load_dwordx4 v[102:105], v[110:111], off offset:16
	s_nop 0
	global_load_dwordx4 v[110:113], v[110:111], off offset:512
	s_nop 0
	global_load_dwordx4 v[114:117], v[114:115], off
	s_nop 0
	global_load_dwordx4 v[122:125], v[126:127], off offset:528
	global_load_dwordx4 v[118:121], v[126:127], off offset:16
	s_nop 0
	global_load_dwordx4 v[126:129], v[126:127], off offset:512
	s_mov_b64 s[48:49], 0
